# M17 + half-block stagger (s_sleep for waves 4-7) at the start of the hyena conv MFMA stream
# speedup vs baseline: 1.0056x; 1.0010x over previous
.LBB0_722:
	s_or_b64 exec, exec, s[6:7]
	s_lshl_b32 s6, s4, 10
	v_lshlrev_b32_e32 v2, 1, v6
	s_and_b32 s6, s6, 0x400
	v_and_b32_e32 v2, 0xffffff80, v2
	s_waitcnt lgkmcnt(0)
	v_add_u32_e32 v66, s6, v2
	v_sub_u32_e32 v2, 0, v6
	v_and_b32_e32 v114, 31, v6
	v_and_b32_e32 v2, 3, v2
	v_mul_u32_u24_e32 v3, 0x2040, v2
	v_add_u32_e32 v2, v2, v114
	v_bfe_u32 v68, v6, 5, 1
	v_or_b32_e32 v2, v66, v2
	v_lshlrev_b32_e32 v4, 4, v68
	v_lshlrev_b32_e32 v2, 1, v2
	v_sub_u32_e32 v2, v4, v2
	v_add3_u32 v67, 0, v2, v3
	v_add_u32_e32 v2, 0x19140, v67
	s_barrier
	v_readfirstlane_b32 s98, v0
	s_bitcmp1_b32 s98, 8
	s_cbranch_scc0 .Lconv_nostag
	s_sleep 3
.Lconv_nostag:
	ds_read2_b64 v[70:73], v2 offset1:1
	v_min_u32_e32 v2, 23, v114
	v_mul_u32_u24_e32 v2, 0x1010, v2
	v_add3_u32 v69, 0, v2, v4
	v_add_u32_e32 v2, 0x19160, v67
	ds_read_b128 v[50:53], v69
	ds_read2_b64 v[74:77], v2 offset1:1
	ds_read_b128 v[78:81], v69 offset:32
	v_add_u32_e32 v2, 0x19100, v67
	v_add_u32_e32 v54, 0x190e0, v67
	ds_read2_b64 v[82:85], v2 offset1:1
	ds_read2_b64 v[54:57], v54 offset1:1
	v_add_u32_e32 v2, 0x19120, v67
	v_add_u32_e32 v58, 0x19180, v67
	ds_read2_b64 v[86:89], v2 offset1:1
	ds_read2_b64 v[90:93], v58 offset1:1
	v_add_u32_e32 v2, 0x190c0, v67
	ds_read2_b64 v[2:5], v2 offset1:1
	ds_read_b128 v[98:101], v69 offset:96
	s_waitcnt lgkmcnt(1)
	v_mfma_f32_32x32x16_bf16 v[2:17], v[2:5], v[50:53], 0
	v_add_u32_e32 v94, 0x191a0, v67
	ds_read2_b64 v[94:97], v94 offset1:1
	v_cmp_gt_u32_e32 vcc, 24, v114
	v_mfma_f32_32x32x16_bf16 v[34:49], v[70:73], v[50:53], 0
	v_mfma_f32_32x32x16_bf16 v[18:33], v[82:85], v[50:53], 0
	v_mfma_f32_32x32x16_bf16 v[2:17], v[54:57], v[78:81], v[2:17]
	v_mfma_f32_32x32x16_bf16 v[50:65], v[90:93], v[50:53], 0
	v_mfma_f32_32x32x16_bf16 v[34:49], v[74:77], v[78:81], v[34:49]
	v_mfma_f32_32x32x16_bf16 v[18:33], v[86:89], v[78:81], v[18:33]
	s_waitcnt lgkmcnt(0)
	v_mfma_f32_32x32x16_bf16 v[50:65], v[94:97], v[78:81], v[50:65]
	ds_read_b128 v[78:81], v69 offset:64
	s_waitcnt lgkmcnt(0)
	v_mfma_f32_32x32x16_bf16 v[2:17], v[82:85], v[78:81], v[2:17]
	v_add_u32_e32 v82, 0x191c0, v67
	ds_read2_b64 v[82:85], v82 offset1:1
	v_mfma_f32_32x32x16_bf16 v[2:17], v[86:89], v[98:101], v[2:17]
	v_add_u32_e32 v86, 0x191e0, v67
	v_mfma_f32_32x32x16_bf16 v[34:49], v[90:93], v[78:81], v[34:49]
	v_mfma_f32_32x32x16_bf16 v[18:33], v[70:73], v[78:81], v[18:33]
	s_waitcnt lgkmcnt(0)
	v_mfma_f32_32x32x16_bf16 v[50:65], v[82:85], v[78:81], v[50:65]
	ds_read2_b64 v[78:81], v86 offset1:1
	ds_read_b128 v[86:89], v69 offset:128
	v_mfma_f32_32x32x16_bf16 v[34:49], v[94:97], v[98:101], v[34:49]
	v_mfma_f32_32x32x16_bf16 v[18:33], v[74:77], v[98:101], v[18:33]
	s_waitcnt lgkmcnt(1)
	v_mfma_f32_32x32x16_bf16 v[50:65], v[78:81], v[98:101], v[50:65]
	ds_read_b128 v[98:101], v69 offset:160
	s_waitcnt lgkmcnt(1)
	v_mfma_f32_32x32x16_bf16 v[2:17], v[70:73], v[86:89], v[2:17]
	v_add_u32_e32 v70, 0x19200, v67
	ds_read2_b64 v[70:73], v70 offset1:1
	s_waitcnt lgkmcnt(1)
	v_mfma_f32_32x32x16_bf16 v[2:17], v[74:77], v[98:101], v[2:17]
	v_add_u32_e32 v74, 0x19220, v67
	ds_read2_b64 v[74:77], v74 offset1:1
	v_mfma_f32_32x32x16_bf16 v[34:49], v[82:85], v[86:89], v[34:49]
	v_mfma_f32_32x32x16_bf16 v[18:33], v[90:93], v[86:89], v[18:33]
	s_waitcnt lgkmcnt(1)
	v_mfma_f32_32x32x16_bf16 v[50:65], v[70:73], v[86:89], v[50:65]
	ds_read_b128 v[86:89], v69 offset:192
	v_mfma_f32_32x32x16_bf16 v[34:49], v[78:81], v[98:101], v[34:49]
	v_mfma_f32_32x32x16_bf16 v[18:33], v[94:97], v[98:101], v[18:33]
	s_waitcnt lgkmcnt(1)
	v_mfma_f32_32x32x16_bf16 v[50:65], v[74:77], v[98:101], v[50:65]
	ds_read_b128 v[98:101], v69 offset:224
	s_waitcnt lgkmcnt(1)
	v_mfma_f32_32x32x16_bf16 v[2:17], v[90:93], v[86:89], v[2:17]
	v_add_u32_e32 v90, 0x19240, v67
	ds_read2_b64 v[90:93], v90 offset1:1
	s_waitcnt lgkmcnt(1)
	v_mfma_f32_32x32x16_bf16 v[2:17], v[94:97], v[98:101], v[2:17]
	v_add_u32_e32 v94, 0x19260, v67
	v_mfma_f32_32x32x16_bf16 v[34:49], v[70:73], v[86:89], v[34:49]
	v_mfma_f32_32x32x16_bf16 v[18:33], v[82:85], v[86:89], v[18:33]
	s_waitcnt lgkmcnt(0)
	v_mfma_f32_32x32x16_bf16 v[50:65], v[90:93], v[86:89], v[50:65]
	ds_read2_b64 v[86:89], v94 offset1:1
	ds_read_b128 v[94:97], v69 offset:256
	v_mfma_f32_32x32x16_bf16 v[34:49], v[74:77], v[98:101], v[34:49]
	v_mfma_f32_32x32x16_bf16 v[18:33], v[78:81], v[98:101], v[18:33]
	s_waitcnt lgkmcnt(1)
	v_mfma_f32_32x32x16_bf16 v[50:65], v[86:89], v[98:101], v[50:65]
	ds_read_b128 v[98:101], v69 offset:288
	s_waitcnt lgkmcnt(1)
	v_mfma_f32_32x32x16_bf16 v[2:17], v[82:85], v[94:97], v[2:17]
	v_add_u32_e32 v82, 0x19280, v67
	s_waitcnt lgkmcnt(0)
	v_mfma_f32_32x32x16_bf16 v[2:17], v[78:81], v[98:101], v[2:17]
	ds_read2_b64 v[78:81], v82 offset1:1
	v_add_u32_e32 v82, 0x192a0, v67
	ds_read2_b64 v[82:85], v82 offset1:1
	v_mfma_f32_32x32x16_bf16 v[34:49], v[90:93], v[94:97], v[34:49]
	v_mfma_f32_32x32x16_bf16 v[18:33], v[70:73], v[94:97], v[18:33]
	s_waitcnt lgkmcnt(1)
	v_mfma_f32_32x32x16_bf16 v[50:65], v[78:81], v[94:97], v[50:65]
	ds_read_b128 v[94:97], v69 offset:320
	v_mfma_f32_32x32x16_bf16 v[34:49], v[86:89], v[98:101], v[34:49]
	v_mfma_f32_32x32x16_bf16 v[18:33], v[74:77], v[98:101], v[18:33]
	s_waitcnt lgkmcnt(1)
	v_mfma_f32_32x32x16_bf16 v[50:65], v[82:85], v[98:101], v[50:65]
	ds_read_b128 v[98:101], v69 offset:352
	s_waitcnt lgkmcnt(1)
	v_mfma_f32_32x32x16_bf16 v[2:17], v[70:73], v[94:97], v[2:17]
	v_add_u32_e32 v70, 0x192c0, v67
	ds_read2_b64 v[70:73], v70 offset1:1
	s_waitcnt lgkmcnt(1)
	v_mfma_f32_32x32x16_bf16 v[2:17], v[74:77], v[98:101], v[2:17]
	v_add_u32_e32 v74, 0x192e0, v67
	ds_read2_b64 v[74:77], v74 offset1:1
	v_mfma_f32_32x32x16_bf16 v[34:49], v[78:81], v[94:97], v[34:49]
	v_mfma_f32_32x32x16_bf16 v[18:33], v[90:93], v[94:97], v[18:33]
	s_waitcnt lgkmcnt(1)
	v_mfma_f32_32x32x16_bf16 v[50:65], v[70:73], v[94:97], v[50:65]
	ds_read_b128 v[94:97], v69 offset:384
	v_mfma_f32_32x32x16_bf16 v[34:49], v[82:85], v[98:101], v[34:49]
	v_mfma_f32_32x32x16_bf16 v[18:33], v[86:89], v[98:101], v[18:33]
	s_waitcnt lgkmcnt(1)
	v_mfma_f32_32x32x16_bf16 v[50:65], v[74:77], v[98:101], v[50:65]
	ds_read_b128 v[98:101], v69 offset:416
	s_waitcnt lgkmcnt(1)
	v_mfma_f32_32x32x16_bf16 v[2:17], v[90:93], v[94:97], v[2:17]
	v_add_u32_e32 v90, 0x19300, v67
	s_waitcnt lgkmcnt(0)
	v_mfma_f32_32x32x16_bf16 v[2:17], v[86:89], v[98:101], v[2:17]
	ds_read2_b64 v[86:89], v90 offset1:1
	v_add_u32_e32 v90, 0x19320, v67
	ds_read2_b64 v[90:93], v90 offset1:1
	v_mfma_f32_32x32x16_bf16 v[34:49], v[70:73], v[94:97], v[34:49]
	v_mfma_f32_32x32x16_bf16 v[18:33], v[78:81], v[94:97], v[18:33]
	s_waitcnt lgkmcnt(1)
	v_mfma_f32_32x32x16_bf16 v[50:65], v[86:89], v[94:97], v[50:65]
	ds_read_b128 v[94:97], v69 offset:448
	v_mfma_f32_32x32x16_bf16 v[34:49], v[74:77], v[98:101], v[34:49]
	v_mfma_f32_32x32x16_bf16 v[18:33], v[82:85], v[98:101], v[18:33]
	s_waitcnt lgkmcnt(1)
	v_mfma_f32_32x32x16_bf16 v[50:65], v[90:93], v[98:101], v[50:65]
	ds_read_b128 v[98:101], v69 offset:480
	s_waitcnt lgkmcnt(1)
	v_mfma_f32_32x32x16_bf16 v[2:17], v[78:81], v[94:97], v[2:17]
	v_add_u32_e32 v78, 0x19340, v67
	ds_read2_b64 v[78:81], v78 offset1:1
	s_waitcnt lgkmcnt(1)
	v_mfma_f32_32x32x16_bf16 v[2:17], v[82:85], v[98:101], v[2:17]
	v_add_u32_e32 v82, 0x19360, v67
	ds_read2_b64 v[82:85], v82 offset1:1
	v_mfma_f32_32x32x16_bf16 v[34:49], v[86:89], v[94:97], v[34:49]
	v_mfma_f32_32x32x16_bf16 v[18:33], v[70:73], v[94:97], v[18:33]
	s_waitcnt lgkmcnt(1)
	v_mfma_f32_32x32x16_bf16 v[50:65], v[78:81], v[94:97], v[50:65]
	ds_read_b128 v[94:97], v69 offset:512
	v_mfma_f32_32x32x16_bf16 v[34:49], v[90:93], v[98:101], v[34:49]
	v_mfma_f32_32x32x16_bf16 v[18:33], v[74:77], v[98:101], v[18:33]
	s_waitcnt lgkmcnt(1)
	v_mfma_f32_32x32x16_bf16 v[50:65], v[82:85], v[98:101], v[50:65]
	ds_read_b128 v[98:101], v69 offset:544
	s_waitcnt lgkmcnt(1)
	v_mfma_f32_32x32x16_bf16 v[2:17], v[70:73], v[94:97], v[2:17]
	v_add_u32_e32 v70, 0x19380, v67
	ds_read2_b64 v[70:73], v70 offset1:1
	s_waitcnt lgkmcnt(1)
	v_mfma_f32_32x32x16_bf16 v[2:17], v[74:77], v[98:101], v[2:17]
	v_add_u32_e32 v74, 0x193a0, v67
	ds_read2_b64 v[74:77], v74 offset1:1
	v_mfma_f32_32x32x16_bf16 v[34:49], v[78:81], v[94:97], v[34:49]
	v_mfma_f32_32x32x16_bf16 v[18:33], v[86:89], v[94:97], v[18:33]
	s_waitcnt lgkmcnt(1)
	v_mfma_f32_32x32x16_bf16 v[50:65], v[70:73], v[94:97], v[50:65]
	ds_read_b128 v[94:97], v69 offset:576
	v_mfma_f32_32x32x16_bf16 v[34:49], v[82:85], v[98:101], v[34:49]
	v_mfma_f32_32x32x16_bf16 v[18:33], v[90:93], v[98:101], v[18:33]
	s_waitcnt lgkmcnt(1)
	v_mfma_f32_32x32x16_bf16 v[50:65], v[74:77], v[98:101], v[50:65]
	ds_read_b128 v[98:101], v69 offset:608
	s_waitcnt lgkmcnt(1)
	v_mfma_f32_32x32x16_bf16 v[2:17], v[86:89], v[94:97], v[2:17]
	v_add_u32_e32 v86, 0x193c0, v67
	ds_read2_b64 v[86:89], v86 offset1:1
	s_waitcnt lgkmcnt(1)
	v_mfma_f32_32x32x16_bf16 v[2:17], v[90:93], v[98:101], v[2:17]
	v_add_u32_e32 v90, 0x193e0, v67
	ds_read2_b64 v[90:93], v90 offset1:1
	v_mfma_f32_32x32x16_bf16 v[34:49], v[70:73], v[94:97], v[34:49]
	v_mfma_f32_32x32x16_bf16 v[18:33], v[78:81], v[94:97], v[18:33]
	s_waitcnt lgkmcnt(1)
	v_mfma_f32_32x32x16_bf16 v[50:65], v[86:89], v[94:97], v[50:65]
	ds_read_b128 v[94:97], v69 offset:640
	v_mfma_f32_32x32x16_bf16 v[34:49], v[74:77], v[98:101], v[34:49]
	v_mfma_f32_32x32x16_bf16 v[18:33], v[82:85], v[98:101], v[18:33]
	s_waitcnt lgkmcnt(1)
	v_mfma_f32_32x32x16_bf16 v[50:65], v[90:93], v[98:101], v[50:65]
	ds_read_b128 v[98:101], v69 offset:672
	s_waitcnt lgkmcnt(1)
	v_mfma_f32_32x32x16_bf16 v[2:17], v[78:81], v[94:97], v[2:17]
	v_add_u32_e32 v78, 0x19400, v67
	ds_read2_b64 v[78:81], v78 offset1:1
	s_waitcnt lgkmcnt(1)
	v_mfma_f32_32x32x16_bf16 v[2:17], v[82:85], v[98:101], v[2:17]
	v_add_u32_e32 v82, 0x19420, v67
	ds_read2_b64 v[82:85], v82 offset1:1
	v_mfma_f32_32x32x16_bf16 v[34:49], v[86:89], v[94:97], v[34:49]
	v_mfma_f32_32x32x16_bf16 v[18:33], v[70:73], v[94:97], v[18:33]
	s_waitcnt lgkmcnt(1)
	v_mfma_f32_32x32x16_bf16 v[50:65], v[78:81], v[94:97], v[50:65]
	ds_read_b128 v[94:97], v69 offset:704
	v_mfma_f32_32x32x16_bf16 v[34:49], v[90:93], v[98:101], v[34:49]
	v_mfma_f32_32x32x16_bf16 v[18:33], v[74:77], v[98:101], v[18:33]
	s_waitcnt lgkmcnt(1)
	v_mfma_f32_32x32x16_bf16 v[50:65], v[82:85], v[98:101], v[50:65]
	ds_read_b128 v[98:101], v69 offset:736
	s_waitcnt lgkmcnt(1)
	v_mfma_f32_32x32x16_bf16 v[2:17], v[70:73], v[94:97], v[2:17]
	v_add_u32_e32 v70, 0x19440, v67
	ds_read2_b64 v[70:73], v70 offset1:1
	s_waitcnt lgkmcnt(1)
	v_mfma_f32_32x32x16_bf16 v[2:17], v[74:77], v[98:101], v[2:17]
	v_add_u32_e32 v74, 0x19460, v67
	ds_read2_b64 v[74:77], v74 offset1:1
	v_mfma_f32_32x32x16_bf16 v[34:49], v[78:81], v[94:97], v[34:49]
	v_mfma_f32_32x32x16_bf16 v[18:33], v[86:89], v[94:97], v[18:33]
	s_waitcnt lgkmcnt(1)
	v_mfma_f32_32x32x16_bf16 v[50:65], v[70:73], v[94:97], v[50:65]
	ds_read_b128 v[94:97], v69 offset:768
	v_mfma_f32_32x32x16_bf16 v[34:49], v[82:85], v[98:101], v[34:49]
	v_mfma_f32_32x32x16_bf16 v[18:33], v[90:93], v[98:101], v[18:33]
	s_waitcnt lgkmcnt(1)
	v_mfma_f32_32x32x16_bf16 v[50:65], v[74:77], v[98:101], v[50:65]
	ds_read_b128 v[98:101], v69 offset:800
	s_waitcnt lgkmcnt(1)
	v_mfma_f32_32x32x16_bf16 v[2:17], v[86:89], v[94:97], v[2:17]
	v_add_u32_e32 v86, 0x19480, v67
	ds_read2_b64 v[86:89], v86 offset1:1
	s_waitcnt lgkmcnt(1)
	v_mfma_f32_32x32x16_bf16 v[2:17], v[90:93], v[98:101], v[2:17]
	v_add_u32_e32 v90, 0x194a0, v67
	ds_read2_b64 v[90:93], v90 offset1:1
	v_mfma_f32_32x32x16_bf16 v[34:49], v[70:73], v[94:97], v[34:49]
	v_mfma_f32_32x32x16_bf16 v[18:33], v[78:81], v[94:97], v[18:33]
	s_waitcnt lgkmcnt(1)
	v_mfma_f32_32x32x16_bf16 v[50:65], v[86:89], v[94:97], v[50:65]
	ds_read_b128 v[94:97], v69 offset:832
	v_mfma_f32_32x32x16_bf16 v[34:49], v[74:77], v[98:101], v[34:49]
	v_mfma_f32_32x32x16_bf16 v[18:33], v[82:85], v[98:101], v[18:33]
	s_waitcnt lgkmcnt(1)
	v_mfma_f32_32x32x16_bf16 v[50:65], v[90:93], v[98:101], v[50:65]
	ds_read_b128 v[98:101], v69 offset:864
	s_waitcnt lgkmcnt(1)
	v_mfma_f32_32x32x16_bf16 v[2:17], v[78:81], v[94:97], v[2:17]
	v_add_u32_e32 v78, 0x194c0, v67
	ds_read2_b64 v[78:81], v78 offset1:1
	s_waitcnt lgkmcnt(1)
	v_mfma_f32_32x32x16_bf16 v[2:17], v[82:85], v[98:101], v[2:17]
	v_add_u32_e32 v82, 0x194e0, v67
	ds_read2_b64 v[82:85], v82 offset1:1
	v_mfma_f32_32x32x16_bf16 v[34:49], v[86:89], v[94:97], v[34:49]
	v_mfma_f32_32x32x16_bf16 v[18:33], v[70:73], v[94:97], v[18:33]
	s_waitcnt lgkmcnt(1)
	v_mfma_f32_32x32x16_bf16 v[50:65], v[78:81], v[94:97], v[50:65]
	ds_read_b128 v[94:97], v69 offset:896
	v_mfma_f32_32x32x16_bf16 v[34:49], v[90:93], v[98:101], v[34:49]
	v_mfma_f32_32x32x16_bf16 v[18:33], v[74:77], v[98:101], v[18:33]
	s_waitcnt lgkmcnt(1)
	v_mfma_f32_32x32x16_bf16 v[50:65], v[82:85], v[98:101], v[50:65]
	ds_read_b128 v[98:101], v69 offset:928
	s_waitcnt lgkmcnt(1)
	v_mfma_f32_32x32x16_bf16 v[2:17], v[70:73], v[94:97], v[2:17]
	v_add_u32_e32 v70, 0x19500, v67
	ds_read2_b64 v[70:73], v70 offset1:1
	s_waitcnt lgkmcnt(1)
	v_mfma_f32_32x32x16_bf16 v[2:17], v[74:77], v[98:101], v[2:17]
	v_add_u32_e32 v74, 0x19520, v67
	ds_read2_b64 v[74:77], v74 offset1:1
	v_mfma_f32_32x32x16_bf16 v[34:49], v[78:81], v[94:97], v[34:49]
	v_mfma_f32_32x32x16_bf16 v[18:33], v[86:89], v[94:97], v[18:33]
	s_waitcnt lgkmcnt(1)
	v_mfma_f32_32x32x16_bf16 v[50:65], v[70:73], v[94:97], v[50:65]
	ds_read_b128 v[94:97], v69 offset:960
	v_mfma_f32_32x32x16_bf16 v[34:49], v[82:85], v[98:101], v[34:49]
	v_mfma_f32_32x32x16_bf16 v[18:33], v[90:93], v[98:101], v[18:33]
	s_waitcnt lgkmcnt(1)
	v_mfma_f32_32x32x16_bf16 v[50:65], v[74:77], v[98:101], v[50:65]
	ds_read_b128 v[98:101], v69 offset:992
	s_waitcnt lgkmcnt(1)
	v_mfma_f32_32x32x16_bf16 v[2:17], v[86:89], v[94:97], v[2:17]
	v_add_u32_e32 v86, 0x19540, v67
	ds_read2_b64 v[86:89], v86 offset1:1
	s_waitcnt lgkmcnt(1)
	v_mfma_f32_32x32x16_bf16 v[2:17], v[90:93], v[98:101], v[2:17]
	v_add_u32_e32 v90, 0x19560, v67
	ds_read2_b64 v[90:93], v90 offset1:1
	v_mfma_f32_32x32x16_bf16 v[34:49], v[70:73], v[94:97], v[34:49]
	v_mfma_f32_32x32x16_bf16 v[18:33], v[78:81], v[94:97], v[18:33]
	s_waitcnt lgkmcnt(1)
	v_mfma_f32_32x32x16_bf16 v[50:65], v[86:89], v[94:97], v[50:65]
	ds_read_b128 v[94:97], v69 offset:1024
	v_mfma_f32_32x32x16_bf16 v[34:49], v[74:77], v[98:101], v[34:49]
	v_mfma_f32_32x32x16_bf16 v[18:33], v[82:85], v[98:101], v[18:33]
	s_waitcnt lgkmcnt(1)
	v_mfma_f32_32x32x16_bf16 v[50:65], v[90:93], v[98:101], v[50:65]
	ds_read_b128 v[98:101], v69 offset:1056
	s_waitcnt lgkmcnt(1)
	v_mfma_f32_32x32x16_bf16 v[2:17], v[78:81], v[94:97], v[2:17]
	v_add_u32_e32 v78, 0x19580, v67
	ds_read2_b64 v[78:81], v78 offset1:1
	s_waitcnt lgkmcnt(1)
	v_mfma_f32_32x32x16_bf16 v[2:17], v[82:85], v[98:101], v[2:17]
	v_add_u32_e32 v82, 0x195a0, v67
	ds_read2_b64 v[82:85], v82 offset1:1
	v_mfma_f32_32x32x16_bf16 v[34:49], v[86:89], v[94:97], v[34:49]
	v_mfma_f32_32x32x16_bf16 v[18:33], v[70:73], v[94:97], v[18:33]
	s_waitcnt lgkmcnt(1)
	v_mfma_f32_32x32x16_bf16 v[50:65], v[78:81], v[94:97], v[50:65]
	ds_read_b128 v[94:97], v69 offset:1088
	v_mfma_f32_32x32x16_bf16 v[34:49], v[90:93], v[98:101], v[34:49]
	v_mfma_f32_32x32x16_bf16 v[18:33], v[74:77], v[98:101], v[18:33]
	s_waitcnt lgkmcnt(1)
	v_mfma_f32_32x32x16_bf16 v[50:65], v[82:85], v[98:101], v[50:65]
	ds_read_b128 v[98:101], v69 offset:1120
	s_waitcnt lgkmcnt(1)
	v_mfma_f32_32x32x16_bf16 v[2:17], v[70:73], v[94:97], v[2:17]
	v_add_u32_e32 v70, 0x195c0, v67
	ds_read2_b64 v[70:73], v70 offset1:1
	s_waitcnt lgkmcnt(1)
	v_mfma_f32_32x32x16_bf16 v[2:17], v[74:77], v[98:101], v[2:17]
	v_add_u32_e32 v74, 0x195e0, v67
	ds_read2_b64 v[74:77], v74 offset1:1
	v_mfma_f32_32x32x16_bf16 v[34:49], v[78:81], v[94:97], v[34:49]
	v_mfma_f32_32x32x16_bf16 v[18:33], v[86:89], v[94:97], v[18:33]
	s_waitcnt lgkmcnt(1)
	v_mfma_f32_32x32x16_bf16 v[50:65], v[70:73], v[94:97], v[50:65]
	ds_read_b128 v[94:97], v69 offset:1152
	v_mfma_f32_32x32x16_bf16 v[34:49], v[82:85], v[98:101], v[34:49]
	v_mfma_f32_32x32x16_bf16 v[18:33], v[90:93], v[98:101], v[18:33]
	s_waitcnt lgkmcnt(1)
	v_mfma_f32_32x32x16_bf16 v[50:65], v[74:77], v[98:101], v[50:65]
	ds_read_b128 v[98:101], v69 offset:1184
	s_waitcnt lgkmcnt(1)
	v_mfma_f32_32x32x16_bf16 v[2:17], v[86:89], v[94:97], v[2:17]
	v_add_u32_e32 v86, 0x19600, v67
	ds_read2_b64 v[86:89], v86 offset1:1
	s_waitcnt lgkmcnt(1)
	v_mfma_f32_32x32x16_bf16 v[2:17], v[90:93], v[98:101], v[2:17]
	v_add_u32_e32 v90, 0x19620, v67
	ds_read2_b64 v[90:93], v90 offset1:1
	v_mfma_f32_32x32x16_bf16 v[34:49], v[70:73], v[94:97], v[34:49]
	v_mfma_f32_32x32x16_bf16 v[18:33], v[78:81], v[94:97], v[18:33]
	s_waitcnt lgkmcnt(1)
	v_mfma_f32_32x32x16_bf16 v[50:65], v[86:89], v[94:97], v[50:65]
	ds_read_b128 v[94:97], v69 offset:1216
	v_mfma_f32_32x32x16_bf16 v[34:49], v[74:77], v[98:101], v[34:49]
	v_mfma_f32_32x32x16_bf16 v[18:33], v[82:85], v[98:101], v[18:33]
	s_waitcnt lgkmcnt(1)
	v_mfma_f32_32x32x16_bf16 v[50:65], v[90:93], v[98:101], v[50:65]
	ds_read_b128 v[98:101], v69 offset:1248
	s_waitcnt lgkmcnt(1)
	v_mfma_f32_32x32x16_bf16 v[2:17], v[78:81], v[94:97], v[2:17]
	v_add_u32_e32 v78, 0x19640, v67
	ds_read2_b64 v[78:81], v78 offset1:1
	s_waitcnt lgkmcnt(1)
	v_mfma_f32_32x32x16_bf16 v[2:17], v[82:85], v[98:101], v[2:17]
	v_add_u32_e32 v82, 0x19660, v67
	ds_read2_b64 v[82:85], v82 offset1:1
	v_mfma_f32_32x32x16_bf16 v[34:49], v[86:89], v[94:97], v[34:49]
	v_mfma_f32_32x32x16_bf16 v[18:33], v[70:73], v[94:97], v[18:33]
	s_waitcnt lgkmcnt(1)
	v_mfma_f32_32x32x16_bf16 v[50:65], v[78:81], v[94:97], v[50:65]
	ds_read_b128 v[94:97], v69 offset:1280
	v_mfma_f32_32x32x16_bf16 v[34:49], v[90:93], v[98:101], v[34:49]
	v_mfma_f32_32x32x16_bf16 v[18:33], v[74:77], v[98:101], v[18:33]
	s_waitcnt lgkmcnt(1)
	v_mfma_f32_32x32x16_bf16 v[50:65], v[82:85], v[98:101], v[50:65]
	ds_read_b128 v[98:101], v69 offset:1312
	s_waitcnt lgkmcnt(1)
	v_mfma_f32_32x32x16_bf16 v[2:17], v[70:73], v[94:97], v[2:17]
	v_add_u32_e32 v70, 0x19680, v67
	ds_read2_b64 v[70:73], v70 offset1:1
	s_waitcnt lgkmcnt(1)
	v_mfma_f32_32x32x16_bf16 v[2:17], v[74:77], v[98:101], v[2:17]
	v_add_u32_e32 v74, 0x196a0, v67
	ds_read2_b64 v[74:77], v74 offset1:1
	v_mfma_f32_32x32x16_bf16 v[34:49], v[78:81], v[94:97], v[34:49]
	v_mfma_f32_32x32x16_bf16 v[18:33], v[86:89], v[94:97], v[18:33]
	s_waitcnt lgkmcnt(1)
	v_mfma_f32_32x32x16_bf16 v[50:65], v[70:73], v[94:97], v[50:65]
	ds_read_b128 v[94:97], v69 offset:1344
	v_mfma_f32_32x32x16_bf16 v[34:49], v[82:85], v[98:101], v[34:49]
	v_mfma_f32_32x32x16_bf16 v[18:33], v[90:93], v[98:101], v[18:33]
	s_waitcnt lgkmcnt(1)
	v_mfma_f32_32x32x16_bf16 v[50:65], v[74:77], v[98:101], v[50:65]
	ds_read_b128 v[98:101], v69 offset:1376
	s_waitcnt lgkmcnt(1)
	v_mfma_f32_32x32x16_bf16 v[2:17], v[86:89], v[94:97], v[2:17]
	v_add_u32_e32 v86, 0x196c0, v67
	ds_read2_b64 v[86:89], v86 offset1:1
	s_waitcnt lgkmcnt(1)
	v_mfma_f32_32x32x16_bf16 v[2:17], v[90:93], v[98:101], v[2:17]
	v_add_u32_e32 v90, 0x196e0, v67
	ds_read2_b64 v[90:93], v90 offset1:1
	v_mfma_f32_32x32x16_bf16 v[34:49], v[70:73], v[94:97], v[34:49]
	v_mfma_f32_32x32x16_bf16 v[18:33], v[78:81], v[94:97], v[18:33]
	s_waitcnt lgkmcnt(1)
	v_mfma_f32_32x32x16_bf16 v[50:65], v[86:89], v[94:97], v[50:65]
	ds_read_b128 v[94:97], v69 offset:1408
	v_mfma_f32_32x32x16_bf16 v[34:49], v[74:77], v[98:101], v[34:49]
	v_mfma_f32_32x32x16_bf16 v[18:33], v[82:85], v[98:101], v[18:33]
	s_waitcnt lgkmcnt(1)
	v_mfma_f32_32x32x16_bf16 v[50:65], v[90:93], v[98:101], v[50:65]
	ds_read_b128 v[98:101], v69 offset:1440
	s_waitcnt lgkmcnt(1)
	v_mfma_f32_32x32x16_bf16 v[2:17], v[78:81], v[94:97], v[2:17]
	v_add_u32_e32 v78, 0x19700, v67
	ds_read2_b64 v[78:81], v78 offset1:1
	s_waitcnt lgkmcnt(1)
	v_mfma_f32_32x32x16_bf16 v[2:17], v[82:85], v[98:101], v[2:17]
	v_add_u32_e32 v82, 0x19720, v67
	ds_read2_b64 v[82:85], v82 offset1:1
	v_mfma_f32_32x32x16_bf16 v[34:49], v[86:89], v[94:97], v[34:49]
	v_mfma_f32_32x32x16_bf16 v[18:33], v[70:73], v[94:97], v[18:33]
	s_waitcnt lgkmcnt(1)
	v_mfma_f32_32x32x16_bf16 v[50:65], v[78:81], v[94:97], v[50:65]
	ds_read_b128 v[94:97], v69 offset:1472
	v_mfma_f32_32x32x16_bf16 v[34:49], v[90:93], v[98:101], v[34:49]
	v_mfma_f32_32x32x16_bf16 v[18:33], v[74:77], v[98:101], v[18:33]
	s_waitcnt lgkmcnt(1)
	v_mfma_f32_32x32x16_bf16 v[50:65], v[82:85], v[98:101], v[50:65]
	ds_read_b128 v[98:101], v69 offset:1504
	s_waitcnt lgkmcnt(1)
	v_mfma_f32_32x32x16_bf16 v[2:17], v[70:73], v[94:97], v[2:17]
	v_add_u32_e32 v70, 0x19740, v67
	ds_read2_b64 v[70:73], v70 offset1:1
	s_waitcnt lgkmcnt(1)
	v_mfma_f32_32x32x16_bf16 v[2:17], v[74:77], v[98:101], v[2:17]
	v_add_u32_e32 v74, 0x19760, v67
	ds_read2_b64 v[74:77], v74 offset1:1
	v_mfma_f32_32x32x16_bf16 v[34:49], v[78:81], v[94:97], v[34:49]
	v_mfma_f32_32x32x16_bf16 v[18:33], v[86:89], v[94:97], v[18:33]
	s_waitcnt lgkmcnt(1)
	v_mfma_f32_32x32x16_bf16 v[50:65], v[70:73], v[94:97], v[50:65]
	ds_read_b128 v[94:97], v69 offset:1536
	v_mfma_f32_32x32x16_bf16 v[34:49], v[82:85], v[98:101], v[34:49]
	v_mfma_f32_32x32x16_bf16 v[18:33], v[90:93], v[98:101], v[18:33]
	s_waitcnt lgkmcnt(1)
	v_mfma_f32_32x32x16_bf16 v[50:65], v[74:77], v[98:101], v[50:65]
	ds_read_b128 v[98:101], v69 offset:1568
	s_waitcnt lgkmcnt(1)
	v_mfma_f32_32x32x16_bf16 v[2:17], v[86:89], v[94:97], v[2:17]
	v_add_u32_e32 v86, 0x19780, v67
	ds_read2_b64 v[86:89], v86 offset1:1
	s_waitcnt lgkmcnt(1)
	v_mfma_f32_32x32x16_bf16 v[2:17], v[90:93], v[98:101], v[2:17]
	v_add_u32_e32 v90, 0x197a0, v67
	ds_read2_b64 v[90:93], v90 offset1:1
	v_mfma_f32_32x32x16_bf16 v[34:49], v[70:73], v[94:97], v[34:49]
	v_mfma_f32_32x32x16_bf16 v[18:33], v[78:81], v[94:97], v[18:33]
	s_waitcnt lgkmcnt(1)
	v_mfma_f32_32x32x16_bf16 v[50:65], v[86:89], v[94:97], v[50:65]
	ds_read_b128 v[94:97], v69 offset:1600
	v_mfma_f32_32x32x16_bf16 v[34:49], v[74:77], v[98:101], v[34:49]
	v_mfma_f32_32x32x16_bf16 v[18:33], v[82:85], v[98:101], v[18:33]
	s_waitcnt lgkmcnt(1)
	v_mfma_f32_32x32x16_bf16 v[50:65], v[90:93], v[98:101], v[50:65]
	ds_read_b128 v[98:101], v69 offset:1632
	s_waitcnt lgkmcnt(1)
	v_mfma_f32_32x32x16_bf16 v[2:17], v[78:81], v[94:97], v[2:17]
	v_add_u32_e32 v78, 0x197c0, v67
	ds_read2_b64 v[78:81], v78 offset1:1
	s_waitcnt lgkmcnt(1)
	v_mfma_f32_32x32x16_bf16 v[2:17], v[82:85], v[98:101], v[2:17]
	v_add_u32_e32 v82, 0x197e0, v67
	ds_read2_b64 v[82:85], v82 offset1:1
	v_mfma_f32_32x32x16_bf16 v[34:49], v[86:89], v[94:97], v[34:49]
	v_mfma_f32_32x32x16_bf16 v[18:33], v[70:73], v[94:97], v[18:33]
	s_waitcnt lgkmcnt(1)
	v_mfma_f32_32x32x16_bf16 v[50:65], v[78:81], v[94:97], v[50:65]
	ds_read_b128 v[94:97], v69 offset:1664
	v_mfma_f32_32x32x16_bf16 v[34:49], v[90:93], v[98:101], v[34:49]
	v_mfma_f32_32x32x16_bf16 v[18:33], v[74:77], v[98:101], v[18:33]
	s_waitcnt lgkmcnt(1)
	v_mfma_f32_32x32x16_bf16 v[50:65], v[82:85], v[98:101], v[50:65]
	ds_read_b128 v[98:101], v69 offset:1696
	s_waitcnt lgkmcnt(1)
	v_mfma_f32_32x32x16_bf16 v[2:17], v[70:73], v[94:97], v[2:17]
	v_add_u32_e32 v70, 0x19800, v67
	ds_read2_b64 v[70:73], v70 offset1:1
	s_waitcnt lgkmcnt(1)
	v_mfma_f32_32x32x16_bf16 v[2:17], v[74:77], v[98:101], v[2:17]
	v_add_u32_e32 v74, 0x19820, v67
	ds_read2_b64 v[74:77], v74 offset1:1
	v_mfma_f32_32x32x16_bf16 v[34:49], v[78:81], v[94:97], v[34:49]
	v_mfma_f32_32x32x16_bf16 v[18:33], v[86:89], v[94:97], v[18:33]
	s_waitcnt lgkmcnt(1)
	v_mfma_f32_32x32x16_bf16 v[50:65], v[70:73], v[94:97], v[50:65]
	ds_read_b128 v[94:97], v69 offset:1728
	v_mfma_f32_32x32x16_bf16 v[34:49], v[82:85], v[98:101], v[34:49]
	v_mfma_f32_32x32x16_bf16 v[18:33], v[90:93], v[98:101], v[18:33]
	s_waitcnt lgkmcnt(1)
	v_mfma_f32_32x32x16_bf16 v[50:65], v[74:77], v[98:101], v[50:65]
	ds_read_b128 v[98:101], v69 offset:1760
	s_waitcnt lgkmcnt(1)
	v_mfma_f32_32x32x16_bf16 v[2:17], v[86:89], v[94:97], v[2:17]
	v_add_u32_e32 v86, 0x19840, v67
	ds_read2_b64 v[86:89], v86 offset1:1
	s_waitcnt lgkmcnt(1)
	v_mfma_f32_32x32x16_bf16 v[2:17], v[90:93], v[98:101], v[2:17]
	v_add_u32_e32 v90, 0x19860, v67
	ds_read2_b64 v[90:93], v90 offset1:1
	v_mfma_f32_32x32x16_bf16 v[34:49], v[70:73], v[94:97], v[34:49]
	v_mfma_f32_32x32x16_bf16 v[18:33], v[78:81], v[94:97], v[18:33]
	s_waitcnt lgkmcnt(1)
	v_mfma_f32_32x32x16_bf16 v[50:65], v[86:89], v[94:97], v[50:65]
	ds_read_b128 v[94:97], v69 offset:1792
	v_mfma_f32_32x32x16_bf16 v[34:49], v[74:77], v[98:101], v[34:49]
	v_mfma_f32_32x32x16_bf16 v[18:33], v[82:85], v[98:101], v[18:33]
	s_waitcnt lgkmcnt(1)
	v_mfma_f32_32x32x16_bf16 v[50:65], v[90:93], v[98:101], v[50:65]
	ds_read_b128 v[98:101], v69 offset:1824
	s_waitcnt lgkmcnt(1)
	v_mfma_f32_32x32x16_bf16 v[2:17], v[78:81], v[94:97], v[2:17]
	v_add_u32_e32 v78, 0x19880, v67
	ds_read2_b64 v[78:81], v78 offset1:1
	s_waitcnt lgkmcnt(1)
	v_mfma_f32_32x32x16_bf16 v[2:17], v[82:85], v[98:101], v[2:17]
	v_add_u32_e32 v82, 0x198a0, v67
	ds_read2_b64 v[82:85], v82 offset1:1
	v_mfma_f32_32x32x16_bf16 v[34:49], v[86:89], v[94:97], v[34:49]
	v_mfma_f32_32x32x16_bf16 v[18:33], v[70:73], v[94:97], v[18:33]
	s_waitcnt lgkmcnt(1)
	v_mfma_f32_32x32x16_bf16 v[50:65], v[78:81], v[94:97], v[50:65]
	ds_read_b128 v[94:97], v69 offset:1856
	v_mfma_f32_32x32x16_bf16 v[34:49], v[90:93], v[98:101], v[34:49]
	v_mfma_f32_32x32x16_bf16 v[18:33], v[74:77], v[98:101], v[18:33]
	s_waitcnt lgkmcnt(1)
	v_mfma_f32_32x32x16_bf16 v[50:65], v[82:85], v[98:101], v[50:65]
	ds_read_b128 v[98:101], v69 offset:1888
	s_waitcnt lgkmcnt(1)
	v_mfma_f32_32x32x16_bf16 v[2:17], v[70:73], v[94:97], v[2:17]
	v_add_u32_e32 v70, 0x198c0, v67
	ds_read2_b64 v[70:73], v70 offset1:1
	s_waitcnt lgkmcnt(1)
	v_mfma_f32_32x32x16_bf16 v[2:17], v[74:77], v[98:101], v[2:17]
	v_add_u32_e32 v74, 0x198e0, v67
	ds_read2_b64 v[74:77], v74 offset1:1
	v_mfma_f32_32x32x16_bf16 v[34:49], v[78:81], v[94:97], v[34:49]
	v_mfma_f32_32x32x16_bf16 v[18:33], v[86:89], v[94:97], v[18:33]
	s_waitcnt lgkmcnt(1)
	v_mfma_f32_32x32x16_bf16 v[50:65], v[70:73], v[94:97], v[50:65]
	ds_read_b128 v[94:97], v69 offset:1920
	v_mfma_f32_32x32x16_bf16 v[34:49], v[82:85], v[98:101], v[34:49]
	v_mfma_f32_32x32x16_bf16 v[18:33], v[90:93], v[98:101], v[18:33]
	s_waitcnt lgkmcnt(1)
	v_mfma_f32_32x32x16_bf16 v[50:65], v[74:77], v[98:101], v[50:65]
	ds_read_b128 v[98:101], v69 offset:1952
	s_waitcnt lgkmcnt(1)
	v_mfma_f32_32x32x16_bf16 v[2:17], v[86:89], v[94:97], v[2:17]
	v_add_u32_e32 v86, 0x19900, v67
	ds_read2_b64 v[86:89], v86 offset1:1
	s_waitcnt lgkmcnt(1)
	v_mfma_f32_32x32x16_bf16 v[2:17], v[90:93], v[98:101], v[2:17]
	v_add_u32_e32 v90, 0x19920, v67
	ds_read2_b64 v[90:93], v90 offset1:1
	v_mfma_f32_32x32x16_bf16 v[34:49], v[70:73], v[94:97], v[34:49]
	v_mfma_f32_32x32x16_bf16 v[18:33], v[78:81], v[94:97], v[18:33]
	s_waitcnt lgkmcnt(1)
	v_mfma_f32_32x32x16_bf16 v[50:65], v[86:89], v[94:97], v[50:65]
	ds_read_b128 v[94:97], v69 offset:1984
	v_mfma_f32_32x32x16_bf16 v[34:49], v[74:77], v[98:101], v[34:49]
	v_mfma_f32_32x32x16_bf16 v[18:33], v[82:85], v[98:101], v[18:33]
	s_waitcnt lgkmcnt(1)
	v_mfma_f32_32x32x16_bf16 v[50:65], v[90:93], v[98:101], v[50:65]
	ds_read_b128 v[98:101], v69 offset:2016
	s_waitcnt lgkmcnt(1)
	v_mfma_f32_32x32x16_bf16 v[2:17], v[78:81], v[94:97], v[2:17]
	v_add_u32_e32 v78, 0x19940, v67
	ds_read2_b64 v[78:81], v78 offset1:1
	s_waitcnt lgkmcnt(1)
	v_mfma_f32_32x32x16_bf16 v[2:17], v[82:85], v[98:101], v[2:17]
	v_add_u32_e32 v82, 0x19960, v67
	ds_read2_b64 v[82:85], v82 offset1:1
	v_mfma_f32_32x32x16_bf16 v[34:49], v[86:89], v[94:97], v[34:49]
	v_mfma_f32_32x32x16_bf16 v[18:33], v[70:73], v[94:97], v[18:33]
	s_waitcnt lgkmcnt(1)
	v_mfma_f32_32x32x16_bf16 v[50:65], v[78:81], v[94:97], v[50:65]
	ds_read_b128 v[94:97], v69 offset:2048
	v_mfma_f32_32x32x16_bf16 v[34:49], v[90:93], v[98:101], v[34:49]
	v_mfma_f32_32x32x16_bf16 v[18:33], v[74:77], v[98:101], v[18:33]
	s_waitcnt lgkmcnt(1)
	v_mfma_f32_32x32x16_bf16 v[50:65], v[82:85], v[98:101], v[50:65]
	ds_read_b128 v[98:101], v69 offset:2080
	s_waitcnt lgkmcnt(1)
	v_mfma_f32_32x32x16_bf16 v[2:17], v[70:73], v[94:97], v[2:17]
	v_add_u32_e32 v70, 0x19980, v67
	ds_read2_b64 v[70:73], v70 offset1:1
	s_waitcnt lgkmcnt(1)
	v_mfma_f32_32x32x16_bf16 v[2:17], v[74:77], v[98:101], v[2:17]
	v_add_u32_e32 v74, 0x199a0, v67
	ds_read2_b64 v[74:77], v74 offset1:1
	v_mfma_f32_32x32x16_bf16 v[34:49], v[78:81], v[94:97], v[34:49]
	v_mfma_f32_32x32x16_bf16 v[18:33], v[86:89], v[94:97], v[18:33]
	s_waitcnt lgkmcnt(1)
	v_mfma_f32_32x32x16_bf16 v[50:65], v[70:73], v[94:97], v[50:65]
	ds_read_b128 v[94:97], v69 offset:2112
	v_mfma_f32_32x32x16_bf16 v[34:49], v[82:85], v[98:101], v[34:49]
	v_mfma_f32_32x32x16_bf16 v[18:33], v[90:93], v[98:101], v[18:33]
	s_waitcnt lgkmcnt(1)
	v_mfma_f32_32x32x16_bf16 v[50:65], v[74:77], v[98:101], v[50:65]
	ds_read_b128 v[98:101], v69 offset:2144
	s_waitcnt lgkmcnt(1)
	v_mfma_f32_32x32x16_bf16 v[2:17], v[86:89], v[94:97], v[2:17]
	v_add_u32_e32 v86, 0x199c0, v67
	ds_read2_b64 v[86:89], v86 offset1:1
	s_waitcnt lgkmcnt(1)
	v_mfma_f32_32x32x16_bf16 v[2:17], v[90:93], v[98:101], v[2:17]
	v_add_u32_e32 v90, 0x199e0, v67
	ds_read2_b64 v[90:93], v90 offset1:1
	v_mfma_f32_32x32x16_bf16 v[34:49], v[70:73], v[94:97], v[34:49]
	v_mfma_f32_32x32x16_bf16 v[18:33], v[78:81], v[94:97], v[18:33]
	s_waitcnt lgkmcnt(1)
	v_mfma_f32_32x32x16_bf16 v[50:65], v[86:89], v[94:97], v[50:65]
	ds_read_b128 v[94:97], v69 offset:2176
	v_mfma_f32_32x32x16_bf16 v[34:49], v[74:77], v[98:101], v[34:49]
	v_mfma_f32_32x32x16_bf16 v[18:33], v[82:85], v[98:101], v[18:33]
	s_waitcnt lgkmcnt(1)
	v_mfma_f32_32x32x16_bf16 v[50:65], v[90:93], v[98:101], v[50:65]
	ds_read_b128 v[98:101], v69 offset:2208
	s_waitcnt lgkmcnt(1)
	v_mfma_f32_32x32x16_bf16 v[2:17], v[78:81], v[94:97], v[2:17]
	v_add_u32_e32 v78, 0x19a00, v67
	ds_read2_b64 v[78:81], v78 offset1:1
	s_waitcnt lgkmcnt(1)
	v_mfma_f32_32x32x16_bf16 v[2:17], v[82:85], v[98:101], v[2:17]
	v_add_u32_e32 v82, 0x19a20, v67
	ds_read2_b64 v[82:85], v82 offset1:1
	v_mfma_f32_32x32x16_bf16 v[34:49], v[86:89], v[94:97], v[34:49]
	v_mfma_f32_32x32x16_bf16 v[18:33], v[70:73], v[94:97], v[18:33]
	s_waitcnt lgkmcnt(1)
	v_mfma_f32_32x32x16_bf16 v[50:65], v[78:81], v[94:97], v[50:65]
	ds_read_b128 v[94:97], v69 offset:2240
	v_mfma_f32_32x32x16_bf16 v[34:49], v[90:93], v[98:101], v[34:49]
	v_mfma_f32_32x32x16_bf16 v[18:33], v[74:77], v[98:101], v[18:33]
	s_waitcnt lgkmcnt(1)
	v_mfma_f32_32x32x16_bf16 v[50:65], v[82:85], v[98:101], v[50:65]
	ds_read_b128 v[98:101], v69 offset:2272
	s_waitcnt lgkmcnt(1)
	v_mfma_f32_32x32x16_bf16 v[2:17], v[70:73], v[94:97], v[2:17]
	v_add_u32_e32 v70, 0x19a40, v67
	ds_read2_b64 v[70:73], v70 offset1:1
	s_waitcnt lgkmcnt(1)
	v_mfma_f32_32x32x16_bf16 v[2:17], v[74:77], v[98:101], v[2:17]
	v_add_u32_e32 v74, 0x19a60, v67
	ds_read2_b64 v[74:77], v74 offset1:1
	v_mfma_f32_32x32x16_bf16 v[34:49], v[78:81], v[94:97], v[34:49]
	v_mfma_f32_32x32x16_bf16 v[18:33], v[86:89], v[94:97], v[18:33]
	s_waitcnt lgkmcnt(1)
	v_mfma_f32_32x32x16_bf16 v[50:65], v[70:73], v[94:97], v[50:65]
	ds_read_b128 v[94:97], v69 offset:2304
	v_mfma_f32_32x32x16_bf16 v[34:49], v[82:85], v[98:101], v[34:49]
	v_mfma_f32_32x32x16_bf16 v[18:33], v[90:93], v[98:101], v[18:33]
	s_waitcnt lgkmcnt(1)
	v_mfma_f32_32x32x16_bf16 v[50:65], v[74:77], v[98:101], v[50:65]
	ds_read_b128 v[98:101], v69 offset:2336
	s_waitcnt lgkmcnt(1)
	v_mfma_f32_32x32x16_bf16 v[2:17], v[86:89], v[94:97], v[2:17]
	v_add_u32_e32 v86, 0x19a80, v67
	ds_read2_b64 v[86:89], v86 offset1:1
	s_waitcnt lgkmcnt(1)
	v_mfma_f32_32x32x16_bf16 v[2:17], v[90:93], v[98:101], v[2:17]
	v_add_u32_e32 v90, 0x19aa0, v67
	ds_read2_b64 v[90:93], v90 offset1:1
	v_mfma_f32_32x32x16_bf16 v[34:49], v[70:73], v[94:97], v[34:49]
	v_mfma_f32_32x32x16_bf16 v[18:33], v[78:81], v[94:97], v[18:33]
	s_waitcnt lgkmcnt(1)
	v_mfma_f32_32x32x16_bf16 v[50:65], v[86:89], v[94:97], v[50:65]
	ds_read_b128 v[94:97], v69 offset:2368
	v_mfma_f32_32x32x16_bf16 v[34:49], v[74:77], v[98:101], v[34:49]
	v_mfma_f32_32x32x16_bf16 v[18:33], v[82:85], v[98:101], v[18:33]
	s_waitcnt lgkmcnt(1)
	v_mfma_f32_32x32x16_bf16 v[50:65], v[90:93], v[98:101], v[50:65]
	ds_read_b128 v[98:101], v69 offset:2400
	s_waitcnt lgkmcnt(1)
	v_mfma_f32_32x32x16_bf16 v[2:17], v[78:81], v[94:97], v[2:17]
	v_add_u32_e32 v78, 0x19ac0, v67
	ds_read2_b64 v[78:81], v78 offset1:1
	s_waitcnt lgkmcnt(1)
	v_mfma_f32_32x32x16_bf16 v[2:17], v[82:85], v[98:101], v[2:17]
	v_add_u32_e32 v82, 0x19ae0, v67
	ds_read2_b64 v[82:85], v82 offset1:1
	v_mfma_f32_32x32x16_bf16 v[34:49], v[86:89], v[94:97], v[34:49]
	v_mfma_f32_32x32x16_bf16 v[18:33], v[70:73], v[94:97], v[18:33]
	s_waitcnt lgkmcnt(1)
	v_mfma_f32_32x32x16_bf16 v[50:65], v[78:81], v[94:97], v[50:65]
	ds_read_b128 v[94:97], v69 offset:2432
	v_mfma_f32_32x32x16_bf16 v[34:49], v[90:93], v[98:101], v[34:49]
	v_mfma_f32_32x32x16_bf16 v[18:33], v[74:77], v[98:101], v[18:33]
	s_waitcnt lgkmcnt(1)
	v_mfma_f32_32x32x16_bf16 v[50:65], v[82:85], v[98:101], v[50:65]
	ds_read_b128 v[98:101], v69 offset:2464
	s_waitcnt lgkmcnt(1)
	v_mfma_f32_32x32x16_bf16 v[2:17], v[70:73], v[94:97], v[2:17]
	v_add_u32_e32 v70, 0x19b00, v67
	ds_read2_b64 v[70:73], v70 offset1:1
	s_waitcnt lgkmcnt(1)
	v_mfma_f32_32x32x16_bf16 v[2:17], v[74:77], v[98:101], v[2:17]
	v_add_u32_e32 v74, 0x19b20, v67
	ds_read2_b64 v[74:77], v74 offset1:1
	v_mfma_f32_32x32x16_bf16 v[34:49], v[78:81], v[94:97], v[34:49]
	v_mfma_f32_32x32x16_bf16 v[18:33], v[86:89], v[94:97], v[18:33]
	s_waitcnt lgkmcnt(1)
	v_mfma_f32_32x32x16_bf16 v[50:65], v[70:73], v[94:97], v[50:65]
	ds_read_b128 v[94:97], v69 offset:2496
	v_mfma_f32_32x32x16_bf16 v[34:49], v[82:85], v[98:101], v[34:49]
	v_mfma_f32_32x32x16_bf16 v[18:33], v[90:93], v[98:101], v[18:33]
	s_waitcnt lgkmcnt(1)
	v_mfma_f32_32x32x16_bf16 v[50:65], v[74:77], v[98:101], v[50:65]
	ds_read_b128 v[98:101], v69 offset:2528
	s_waitcnt lgkmcnt(1)
	v_mfma_f32_32x32x16_bf16 v[2:17], v[86:89], v[94:97], v[2:17]
	v_add_u32_e32 v86, 0x19b40, v67
	ds_read2_b64 v[86:89], v86 offset1:1
	s_waitcnt lgkmcnt(1)
	v_mfma_f32_32x32x16_bf16 v[2:17], v[90:93], v[98:101], v[2:17]
	v_add_u32_e32 v90, 0x19b60, v67
	ds_read2_b64 v[90:93], v90 offset1:1
	v_mfma_f32_32x32x16_bf16 v[34:49], v[70:73], v[94:97], v[34:49]
	v_mfma_f32_32x32x16_bf16 v[18:33], v[78:81], v[94:97], v[18:33]
	s_waitcnt lgkmcnt(1)
	v_mfma_f32_32x32x16_bf16 v[50:65], v[86:89], v[94:97], v[50:65]
	ds_read_b128 v[94:97], v69 offset:2560
	v_mfma_f32_32x32x16_bf16 v[34:49], v[74:77], v[98:101], v[34:49]
	v_mfma_f32_32x32x16_bf16 v[18:33], v[82:85], v[98:101], v[18:33]
	s_waitcnt lgkmcnt(1)
	v_mfma_f32_32x32x16_bf16 v[50:65], v[90:93], v[98:101], v[50:65]
	ds_read_b128 v[98:101], v69 offset:2592
	s_waitcnt lgkmcnt(1)
	v_mfma_f32_32x32x16_bf16 v[2:17], v[78:81], v[94:97], v[2:17]
	v_add_u32_e32 v78, 0x19b80, v67
	ds_read2_b64 v[78:81], v78 offset1:1
	s_waitcnt lgkmcnt(1)
	v_mfma_f32_32x32x16_bf16 v[2:17], v[82:85], v[98:101], v[2:17]
	v_add_u32_e32 v82, 0x19ba0, v67
	ds_read2_b64 v[82:85], v82 offset1:1
	v_mfma_f32_32x32x16_bf16 v[34:49], v[86:89], v[94:97], v[34:49]
	v_mfma_f32_32x32x16_bf16 v[18:33], v[70:73], v[94:97], v[18:33]
	s_waitcnt lgkmcnt(1)
	v_mfma_f32_32x32x16_bf16 v[50:65], v[78:81], v[94:97], v[50:65]
	ds_read_b128 v[94:97], v69 offset:2624
	v_mfma_f32_32x32x16_bf16 v[34:49], v[90:93], v[98:101], v[34:49]
	v_mfma_f32_32x32x16_bf16 v[18:33], v[74:77], v[98:101], v[18:33]
	s_waitcnt lgkmcnt(1)
	v_mfma_f32_32x32x16_bf16 v[50:65], v[82:85], v[98:101], v[50:65]
	ds_read_b128 v[98:101], v69 offset:2656
	s_waitcnt lgkmcnt(1)
	v_mfma_f32_32x32x16_bf16 v[2:17], v[70:73], v[94:97], v[2:17]
	v_add_u32_e32 v70, 0x19bc0, v67
	ds_read2_b64 v[70:73], v70 offset1:1
	s_waitcnt lgkmcnt(1)
	v_mfma_f32_32x32x16_bf16 v[2:17], v[74:77], v[98:101], v[2:17]
	v_add_u32_e32 v74, 0x19be0, v67
	ds_read2_b64 v[74:77], v74 offset1:1
	v_mfma_f32_32x32x16_bf16 v[34:49], v[78:81], v[94:97], v[34:49]
	v_mfma_f32_32x32x16_bf16 v[18:33], v[86:89], v[94:97], v[18:33]
	s_waitcnt lgkmcnt(1)
	v_mfma_f32_32x32x16_bf16 v[50:65], v[70:73], v[94:97], v[50:65]
	ds_read_b128 v[94:97], v69 offset:2688
	v_mfma_f32_32x32x16_bf16 v[34:49], v[82:85], v[98:101], v[34:49]
	v_mfma_f32_32x32x16_bf16 v[18:33], v[90:93], v[98:101], v[18:33]
	s_waitcnt lgkmcnt(1)
	v_mfma_f32_32x32x16_bf16 v[50:65], v[74:77], v[98:101], v[50:65]
	ds_read_b128 v[98:101], v69 offset:2720
	s_waitcnt lgkmcnt(1)
	v_mfma_f32_32x32x16_bf16 v[2:17], v[86:89], v[94:97], v[2:17]
	v_add_u32_e32 v86, 0x19c00, v67
	ds_read2_b64 v[86:89], v86 offset1:1
	s_waitcnt lgkmcnt(1)
	v_mfma_f32_32x32x16_bf16 v[2:17], v[90:93], v[98:101], v[2:17]
	v_add_u32_e32 v90, 0x19c20, v67
	ds_read2_b64 v[90:93], v90 offset1:1
	v_mfma_f32_32x32x16_bf16 v[34:49], v[70:73], v[94:97], v[34:49]
	v_mfma_f32_32x32x16_bf16 v[18:33], v[78:81], v[94:97], v[18:33]
	s_waitcnt lgkmcnt(1)
	v_mfma_f32_32x32x16_bf16 v[50:65], v[86:89], v[94:97], v[50:65]
	ds_read_b128 v[94:97], v69 offset:2752
	v_mfma_f32_32x32x16_bf16 v[34:49], v[74:77], v[98:101], v[34:49]
	v_mfma_f32_32x32x16_bf16 v[18:33], v[82:85], v[98:101], v[18:33]
	s_waitcnt lgkmcnt(1)
	v_mfma_f32_32x32x16_bf16 v[50:65], v[90:93], v[98:101], v[50:65]
	ds_read_b128 v[98:101], v69 offset:2784
	s_waitcnt lgkmcnt(1)
	v_mfma_f32_32x32x16_bf16 v[2:17], v[78:81], v[94:97], v[2:17]
	v_add_u32_e32 v78, 0x19c40, v67
	ds_read2_b64 v[78:81], v78 offset1:1
	s_waitcnt lgkmcnt(1)
	v_mfma_f32_32x32x16_bf16 v[2:17], v[82:85], v[98:101], v[2:17]
	v_add_u32_e32 v82, 0x19c60, v67
	ds_read2_b64 v[82:85], v82 offset1:1
	v_mfma_f32_32x32x16_bf16 v[34:49], v[86:89], v[94:97], v[34:49]
	v_mfma_f32_32x32x16_bf16 v[18:33], v[70:73], v[94:97], v[18:33]
	s_waitcnt lgkmcnt(1)
	v_mfma_f32_32x32x16_bf16 v[50:65], v[78:81], v[94:97], v[50:65]
	ds_read_b128 v[94:97], v69 offset:2816
	v_mfma_f32_32x32x16_bf16 v[34:49], v[90:93], v[98:101], v[34:49]
	v_mfma_f32_32x32x16_bf16 v[18:33], v[74:77], v[98:101], v[18:33]
	s_waitcnt lgkmcnt(1)
	v_mfma_f32_32x32x16_bf16 v[50:65], v[82:85], v[98:101], v[50:65]
	ds_read_b128 v[98:101], v69 offset:2848
	s_waitcnt lgkmcnt(1)
	v_mfma_f32_32x32x16_bf16 v[2:17], v[70:73], v[94:97], v[2:17]
	v_add_u32_e32 v70, 0x19c80, v67
	ds_read2_b64 v[70:73], v70 offset1:1
	s_waitcnt lgkmcnt(1)
	v_mfma_f32_32x32x16_bf16 v[2:17], v[74:77], v[98:101], v[2:17]
	v_add_u32_e32 v74, 0x19ca0, v67
	ds_read2_b64 v[74:77], v74 offset1:1
	v_mfma_f32_32x32x16_bf16 v[34:49], v[78:81], v[94:97], v[34:49]
	v_mfma_f32_32x32x16_bf16 v[18:33], v[86:89], v[94:97], v[18:33]
	s_waitcnt lgkmcnt(1)
	v_mfma_f32_32x32x16_bf16 v[50:65], v[70:73], v[94:97], v[50:65]
	ds_read_b128 v[94:97], v69 offset:2880
	v_mfma_f32_32x32x16_bf16 v[34:49], v[82:85], v[98:101], v[34:49]
	v_mfma_f32_32x32x16_bf16 v[18:33], v[90:93], v[98:101], v[18:33]
	s_waitcnt lgkmcnt(1)
	v_mfma_f32_32x32x16_bf16 v[50:65], v[74:77], v[98:101], v[50:65]
	ds_read_b128 v[98:101], v69 offset:2912
	s_waitcnt lgkmcnt(1)
	v_mfma_f32_32x32x16_bf16 v[2:17], v[86:89], v[94:97], v[2:17]
	v_add_u32_e32 v86, 0x19cc0, v67
	ds_read2_b64 v[86:89], v86 offset1:1
	s_waitcnt lgkmcnt(1)
	v_mfma_f32_32x32x16_bf16 v[2:17], v[90:93], v[98:101], v[2:17]
	v_add_u32_e32 v90, 0x19ce0, v67
	ds_read2_b64 v[90:93], v90 offset1:1
	v_mfma_f32_32x32x16_bf16 v[34:49], v[70:73], v[94:97], v[34:49]
	v_mfma_f32_32x32x16_bf16 v[18:33], v[78:81], v[94:97], v[18:33]
	s_waitcnt lgkmcnt(1)
	v_mfma_f32_32x32x16_bf16 v[50:65], v[86:89], v[94:97], v[50:65]
	ds_read_b128 v[94:97], v69 offset:2944
	v_mfma_f32_32x32x16_bf16 v[34:49], v[74:77], v[98:101], v[34:49]
	v_mfma_f32_32x32x16_bf16 v[18:33], v[82:85], v[98:101], v[18:33]
	s_waitcnt lgkmcnt(1)
	v_mfma_f32_32x32x16_bf16 v[50:65], v[90:93], v[98:101], v[50:65]
	ds_read_b128 v[98:101], v69 offset:2976
	s_waitcnt lgkmcnt(1)
	v_mfma_f32_32x32x16_bf16 v[2:17], v[78:81], v[94:97], v[2:17]
	v_add_u32_e32 v78, 0x19d00, v67
	ds_read2_b64 v[78:81], v78 offset1:1
	s_waitcnt lgkmcnt(1)
	v_mfma_f32_32x32x16_bf16 v[2:17], v[82:85], v[98:101], v[2:17]
	v_add_u32_e32 v82, 0x19d20, v67
	ds_read2_b64 v[82:85], v82 offset1:1
	v_mfma_f32_32x32x16_bf16 v[34:49], v[86:89], v[94:97], v[34:49]
	v_mfma_f32_32x32x16_bf16 v[18:33], v[70:73], v[94:97], v[18:33]
	s_waitcnt lgkmcnt(1)
	v_mfma_f32_32x32x16_bf16 v[50:65], v[78:81], v[94:97], v[50:65]
	ds_read_b128 v[94:97], v69 offset:3008
	v_mfma_f32_32x32x16_bf16 v[34:49], v[90:93], v[98:101], v[34:49]
	v_mfma_f32_32x32x16_bf16 v[18:33], v[74:77], v[98:101], v[18:33]
	s_waitcnt lgkmcnt(1)
	v_mfma_f32_32x32x16_bf16 v[50:65], v[82:85], v[98:101], v[50:65]
	ds_read_b128 v[98:101], v69 offset:3040
	s_waitcnt lgkmcnt(1)
	v_mfma_f32_32x32x16_bf16 v[2:17], v[70:73], v[94:97], v[2:17]
	v_add_u32_e32 v70, 0x19d40, v67
	ds_read2_b64 v[70:73], v70 offset1:1
	s_waitcnt lgkmcnt(1)
	v_mfma_f32_32x32x16_bf16 v[2:17], v[74:77], v[98:101], v[2:17]
	v_add_u32_e32 v74, 0x19d60, v67
	ds_read2_b64 v[74:77], v74 offset1:1
	v_mfma_f32_32x32x16_bf16 v[34:49], v[78:81], v[94:97], v[34:49]
	v_mfma_f32_32x32x16_bf16 v[18:33], v[86:89], v[94:97], v[18:33]
	s_waitcnt lgkmcnt(1)
	v_mfma_f32_32x32x16_bf16 v[50:65], v[70:73], v[94:97], v[50:65]
	ds_read_b128 v[94:97], v69 offset:3072
	v_mfma_f32_32x32x16_bf16 v[34:49], v[82:85], v[98:101], v[34:49]
	v_mfma_f32_32x32x16_bf16 v[18:33], v[90:93], v[98:101], v[18:33]
	s_waitcnt lgkmcnt(1)
	v_mfma_f32_32x32x16_bf16 v[50:65], v[74:77], v[98:101], v[50:65]
	ds_read_b128 v[98:101], v69 offset:3104
	s_waitcnt lgkmcnt(1)
	v_mfma_f32_32x32x16_bf16 v[2:17], v[86:89], v[94:97], v[2:17]
	v_add_u32_e32 v86, 0x19d80, v67
	ds_read2_b64 v[86:89], v86 offset1:1
	s_waitcnt lgkmcnt(1)
	v_mfma_f32_32x32x16_bf16 v[2:17], v[90:93], v[98:101], v[2:17]
	v_add_u32_e32 v90, 0x19da0, v67
	ds_read2_b64 v[90:93], v90 offset1:1
	v_mfma_f32_32x32x16_bf16 v[34:49], v[70:73], v[94:97], v[34:49]
	v_mfma_f32_32x32x16_bf16 v[18:33], v[78:81], v[94:97], v[18:33]
	s_waitcnt lgkmcnt(1)
	v_mfma_f32_32x32x16_bf16 v[50:65], v[86:89], v[94:97], v[50:65]
	ds_read_b128 v[94:97], v69 offset:3136
	v_mfma_f32_32x32x16_bf16 v[34:49], v[74:77], v[98:101], v[34:49]
	v_mfma_f32_32x32x16_bf16 v[18:33], v[82:85], v[98:101], v[18:33]
	s_waitcnt lgkmcnt(1)
	v_mfma_f32_32x32x16_bf16 v[50:65], v[90:93], v[98:101], v[50:65]
	ds_read_b128 v[98:101], v69 offset:3168
	s_waitcnt lgkmcnt(1)
	v_mfma_f32_32x32x16_bf16 v[2:17], v[78:81], v[94:97], v[2:17]
	v_add_u32_e32 v78, 0x19dc0, v67
	ds_read2_b64 v[78:81], v78 offset1:1
	s_waitcnt lgkmcnt(1)
	v_mfma_f32_32x32x16_bf16 v[2:17], v[82:85], v[98:101], v[2:17]
	v_add_u32_e32 v82, 0x19de0, v67
	ds_read2_b64 v[82:85], v82 offset1:1
	v_mfma_f32_32x32x16_bf16 v[34:49], v[86:89], v[94:97], v[34:49]
	v_mfma_f32_32x32x16_bf16 v[18:33], v[70:73], v[94:97], v[18:33]
	s_waitcnt lgkmcnt(1)
	v_mfma_f32_32x32x16_bf16 v[50:65], v[78:81], v[94:97], v[50:65]
	ds_read_b128 v[94:97], v69 offset:3200
	v_mfma_f32_32x32x16_bf16 v[34:49], v[90:93], v[98:101], v[34:49]
	v_mfma_f32_32x32x16_bf16 v[18:33], v[74:77], v[98:101], v[18:33]
	s_waitcnt lgkmcnt(1)
	v_mfma_f32_32x32x16_bf16 v[50:65], v[82:85], v[98:101], v[50:65]
	ds_read_b128 v[98:101], v69 offset:3232
	s_waitcnt lgkmcnt(1)
	v_mfma_f32_32x32x16_bf16 v[2:17], v[70:73], v[94:97], v[2:17]
	v_add_u32_e32 v70, 0x19e00, v67
	ds_read2_b64 v[70:73], v70 offset1:1
	s_waitcnt lgkmcnt(1)
	v_mfma_f32_32x32x16_bf16 v[2:17], v[74:77], v[98:101], v[2:17]
	v_add_u32_e32 v74, 0x19e20, v67
	ds_read2_b64 v[74:77], v74 offset1:1
	v_mfma_f32_32x32x16_bf16 v[34:49], v[78:81], v[94:97], v[34:49]
	v_mfma_f32_32x32x16_bf16 v[18:33], v[86:89], v[94:97], v[18:33]
	s_waitcnt lgkmcnt(1)
	v_mfma_f32_32x32x16_bf16 v[50:65], v[70:73], v[94:97], v[50:65]
	ds_read_b128 v[94:97], v69 offset:3264
	v_mfma_f32_32x32x16_bf16 v[34:49], v[82:85], v[98:101], v[34:49]
	v_mfma_f32_32x32x16_bf16 v[18:33], v[90:93], v[98:101], v[18:33]
	s_waitcnt lgkmcnt(1)
	v_mfma_f32_32x32x16_bf16 v[50:65], v[74:77], v[98:101], v[50:65]
	ds_read_b128 v[98:101], v69 offset:3296
	s_waitcnt lgkmcnt(1)
	v_mfma_f32_32x32x16_bf16 v[2:17], v[86:89], v[94:97], v[2:17]
	v_add_u32_e32 v86, 0x19e40, v67
	ds_read2_b64 v[86:89], v86 offset1:1
	s_waitcnt lgkmcnt(1)
	v_mfma_f32_32x32x16_bf16 v[2:17], v[90:93], v[98:101], v[2:17]
	v_add_u32_e32 v90, 0x19e60, v67
	ds_read2_b64 v[90:93], v90 offset1:1
	v_mfma_f32_32x32x16_bf16 v[34:49], v[70:73], v[94:97], v[34:49]
	v_mfma_f32_32x32x16_bf16 v[18:33], v[78:81], v[94:97], v[18:33]
	s_waitcnt lgkmcnt(1)
	v_mfma_f32_32x32x16_bf16 v[50:65], v[86:89], v[94:97], v[50:65]
	ds_read_b128 v[94:97], v69 offset:3328
	v_mfma_f32_32x32x16_bf16 v[34:49], v[74:77], v[98:101], v[34:49]
	v_mfma_f32_32x32x16_bf16 v[18:33], v[82:85], v[98:101], v[18:33]
	s_waitcnt lgkmcnt(1)
	v_mfma_f32_32x32x16_bf16 v[50:65], v[90:93], v[98:101], v[50:65]
	ds_read_b128 v[98:101], v69 offset:3360
	s_waitcnt lgkmcnt(1)
	v_mfma_f32_32x32x16_bf16 v[2:17], v[78:81], v[94:97], v[2:17]
	v_add_u32_e32 v78, 0x19e80, v67
	ds_read2_b64 v[78:81], v78 offset1:1
	s_waitcnt lgkmcnt(1)
	v_mfma_f32_32x32x16_bf16 v[2:17], v[82:85], v[98:101], v[2:17]
	v_add_u32_e32 v82, 0x19ea0, v67
	ds_read2_b64 v[82:85], v82 offset1:1
	v_mfma_f32_32x32x16_bf16 v[34:49], v[86:89], v[94:97], v[34:49]
	v_mfma_f32_32x32x16_bf16 v[18:33], v[70:73], v[94:97], v[18:33]
	s_waitcnt lgkmcnt(1)
	v_mfma_f32_32x32x16_bf16 v[50:65], v[78:81], v[94:97], v[50:65]
	ds_read_b128 v[94:97], v69 offset:3392
	v_mfma_f32_32x32x16_bf16 v[34:49], v[90:93], v[98:101], v[34:49]
	v_mfma_f32_32x32x16_bf16 v[18:33], v[74:77], v[98:101], v[18:33]
	s_waitcnt lgkmcnt(1)
	v_mfma_f32_32x32x16_bf16 v[50:65], v[82:85], v[98:101], v[50:65]
	ds_read_b128 v[98:101], v69 offset:3424
	s_waitcnt lgkmcnt(1)
	v_mfma_f32_32x32x16_bf16 v[2:17], v[70:73], v[94:97], v[2:17]
	v_add_u32_e32 v70, 0x19ec0, v67
	ds_read2_b64 v[70:73], v70 offset1:1
	s_waitcnt lgkmcnt(1)
	v_mfma_f32_32x32x16_bf16 v[2:17], v[74:77], v[98:101], v[2:17]
	v_add_u32_e32 v74, 0x19ee0, v67
	ds_read2_b64 v[74:77], v74 offset1:1
	v_mfma_f32_32x32x16_bf16 v[34:49], v[78:81], v[94:97], v[34:49]
	v_mfma_f32_32x32x16_bf16 v[18:33], v[86:89], v[94:97], v[18:33]
	s_waitcnt lgkmcnt(1)
	v_mfma_f32_32x32x16_bf16 v[50:65], v[70:73], v[94:97], v[50:65]
	ds_read_b128 v[94:97], v69 offset:3456
	v_mfma_f32_32x32x16_bf16 v[34:49], v[82:85], v[98:101], v[34:49]
	v_mfma_f32_32x32x16_bf16 v[18:33], v[90:93], v[98:101], v[18:33]
	s_waitcnt lgkmcnt(1)
	v_mfma_f32_32x32x16_bf16 v[50:65], v[74:77], v[98:101], v[50:65]
	ds_read_b128 v[98:101], v69 offset:3488
	s_waitcnt lgkmcnt(1)
	v_mfma_f32_32x32x16_bf16 v[2:17], v[86:89], v[94:97], v[2:17]
	v_add_u32_e32 v86, 0x19f00, v67
	ds_read2_b64 v[86:89], v86 offset1:1
	s_waitcnt lgkmcnt(1)
	v_mfma_f32_32x32x16_bf16 v[2:17], v[90:93], v[98:101], v[2:17]
	v_add_u32_e32 v90, 0x19f20, v67
	ds_read2_b64 v[90:93], v90 offset1:1
	v_mfma_f32_32x32x16_bf16 v[34:49], v[70:73], v[94:97], v[34:49]
	v_mfma_f32_32x32x16_bf16 v[18:33], v[78:81], v[94:97], v[18:33]
	s_waitcnt lgkmcnt(1)
	v_mfma_f32_32x32x16_bf16 v[50:65], v[86:89], v[94:97], v[50:65]
	ds_read_b128 v[94:97], v69 offset:3520
	v_mfma_f32_32x32x16_bf16 v[34:49], v[74:77], v[98:101], v[34:49]
	v_mfma_f32_32x32x16_bf16 v[18:33], v[82:85], v[98:101], v[18:33]
	s_waitcnt lgkmcnt(1)
	v_mfma_f32_32x32x16_bf16 v[50:65], v[90:93], v[98:101], v[50:65]
	ds_read_b128 v[98:101], v69 offset:3552
	s_waitcnt lgkmcnt(1)
	v_mfma_f32_32x32x16_bf16 v[2:17], v[78:81], v[94:97], v[2:17]
	v_add_u32_e32 v78, 0x19f40, v67
	ds_read2_b64 v[78:81], v78 offset1:1
	s_waitcnt lgkmcnt(1)
	v_mfma_f32_32x32x16_bf16 v[2:17], v[82:85], v[98:101], v[2:17]
	v_add_u32_e32 v82, 0x19f60, v67
	ds_read2_b64 v[82:85], v82 offset1:1
	v_mfma_f32_32x32x16_bf16 v[34:49], v[86:89], v[94:97], v[34:49]
	v_mfma_f32_32x32x16_bf16 v[18:33], v[70:73], v[94:97], v[18:33]
	s_waitcnt lgkmcnt(1)
	v_mfma_f32_32x32x16_bf16 v[50:65], v[78:81], v[94:97], v[50:65]
	ds_read_b128 v[94:97], v69 offset:3584
	v_mfma_f32_32x32x16_bf16 v[34:49], v[90:93], v[98:101], v[34:49]
	v_mfma_f32_32x32x16_bf16 v[18:33], v[74:77], v[98:101], v[18:33]
	s_waitcnt lgkmcnt(1)
	v_mfma_f32_32x32x16_bf16 v[50:65], v[82:85], v[98:101], v[50:65]
	ds_read_b128 v[98:101], v69 offset:3616
	s_waitcnt lgkmcnt(1)
	v_mfma_f32_32x32x16_bf16 v[2:17], v[70:73], v[94:97], v[2:17]
	v_add_u32_e32 v70, 0x19f80, v67
	ds_read2_b64 v[70:73], v70 offset1:1
	s_waitcnt lgkmcnt(1)
	v_mfma_f32_32x32x16_bf16 v[2:17], v[74:77], v[98:101], v[2:17]
	v_add_u32_e32 v74, 0x19fa0, v67
	ds_read2_b64 v[74:77], v74 offset1:1
	v_mfma_f32_32x32x16_bf16 v[34:49], v[78:81], v[94:97], v[34:49]
	v_mfma_f32_32x32x16_bf16 v[18:33], v[86:89], v[94:97], v[18:33]
	s_waitcnt lgkmcnt(1)
	v_mfma_f32_32x32x16_bf16 v[50:65], v[70:73], v[94:97], v[50:65]
	ds_read_b128 v[94:97], v69 offset:3648
	v_mfma_f32_32x32x16_bf16 v[34:49], v[82:85], v[98:101], v[34:49]
	v_mfma_f32_32x32x16_bf16 v[18:33], v[90:93], v[98:101], v[18:33]
	s_waitcnt lgkmcnt(1)
	v_mfma_f32_32x32x16_bf16 v[50:65], v[74:77], v[98:101], v[50:65]
	ds_read_b128 v[98:101], v69 offset:3680
	s_waitcnt lgkmcnt(1)
	v_mfma_f32_32x32x16_bf16 v[2:17], v[86:89], v[94:97], v[2:17]
	v_add_u32_e32 v86, 0x19fc0, v67
	ds_read2_b64 v[86:89], v86 offset1:1
	s_waitcnt lgkmcnt(1)
	v_mfma_f32_32x32x16_bf16 v[2:17], v[90:93], v[98:101], v[2:17]
	v_add_u32_e32 v90, 0x19fe0, v67
	ds_read2_b64 v[90:93], v90 offset1:1
	v_mfma_f32_32x32x16_bf16 v[34:49], v[70:73], v[94:97], v[34:49]
	v_mfma_f32_32x32x16_bf16 v[18:33], v[78:81], v[94:97], v[18:33]
	s_waitcnt lgkmcnt(1)
	v_mfma_f32_32x32x16_bf16 v[50:65], v[86:89], v[94:97], v[50:65]
	ds_read_b128 v[94:97], v69 offset:3712
	v_mfma_f32_32x32x16_bf16 v[34:49], v[74:77], v[98:101], v[34:49]
	v_mfma_f32_32x32x16_bf16 v[18:33], v[82:85], v[98:101], v[18:33]
	s_waitcnt lgkmcnt(1)
	v_mfma_f32_32x32x16_bf16 v[50:65], v[90:93], v[98:101], v[50:65]
	ds_read_b128 v[98:101], v69 offset:3744
	s_waitcnt lgkmcnt(1)
	v_mfma_f32_32x32x16_bf16 v[2:17], v[78:81], v[94:97], v[2:17]
	v_add_u32_e32 v78, 0x1a000, v67
	ds_read2_b64 v[78:81], v78 offset1:1
	v_mfma_f32_32x32x16_bf16 v[34:49], v[86:89], v[94:97], v[34:49]
	s_waitcnt lgkmcnt(1)
	v_mfma_f32_32x32x16_bf16 v[2:17], v[82:85], v[98:101], v[2:17]
	v_add_u32_e32 v82, 0x1a020, v67
	ds_read2_b64 v[82:85], v82 offset1:1
	v_mfma_f32_32x32x16_bf16 v[18:33], v[70:73], v[94:97], v[18:33]
	s_waitcnt lgkmcnt(1)
	v_mfma_f32_32x32x16_bf16 v[50:65], v[78:81], v[94:97], v[50:65]
	ds_read_b128 v[94:97], v69 offset:3776
	v_mfma_f32_32x32x16_bf16 v[34:49], v[90:93], v[98:101], v[34:49]
	v_mfma_f32_32x32x16_bf16 v[18:33], v[74:77], v[98:101], v[18:33]
	s_waitcnt lgkmcnt(1)
	v_mfma_f32_32x32x16_bf16 v[50:65], v[82:85], v[98:101], v[50:65]
	ds_read_b128 v[98:101], v69 offset:3808
	s_waitcnt lgkmcnt(1)
	v_mfma_f32_32x32x16_bf16 v[2:17], v[70:73], v[94:97], v[2:17]
	v_add_u32_e32 v70, 0x1a040, v67
	ds_read2_b64 v[70:73], v70 offset1:1
	v_mfma_f32_32x32x16_bf16 v[34:49], v[78:81], v[94:97], v[34:49]
	s_waitcnt lgkmcnt(1)
	v_mfma_f32_32x32x16_bf16 v[2:17], v[74:77], v[98:101], v[2:17]
	v_add_u32_e32 v74, 0x1a060, v67
	ds_read2_b64 v[74:77], v74 offset1:1
	v_mfma_f32_32x32x16_bf16 v[18:33], v[86:89], v[94:97], v[18:33]
	s_waitcnt lgkmcnt(1)
	v_mfma_f32_32x32x16_bf16 v[50:65], v[70:73], v[94:97], v[50:65]
	ds_read_b128 v[94:97], v69 offset:3840
	v_mfma_f32_32x32x16_bf16 v[34:49], v[82:85], v[98:101], v[34:49]
	v_mfma_f32_32x32x16_bf16 v[18:33], v[90:93], v[98:101], v[18:33]
	s_waitcnt lgkmcnt(1)
	v_mfma_f32_32x32x16_bf16 v[50:65], v[74:77], v[98:101], v[50:65]
	ds_read_b128 v[98:101], v69 offset:3872
	s_waitcnt lgkmcnt(1)
	v_mfma_f32_32x32x16_bf16 v[2:17], v[86:89], v[94:97], v[2:17]
	v_add_u32_e32 v86, 0x1a080, v67
	ds_read2_b64 v[86:89], v86 offset1:1
	v_mfma_f32_32x32x16_bf16 v[34:49], v[70:73], v[94:97], v[34:49]
	s_waitcnt lgkmcnt(1)
	v_mfma_f32_32x32x16_bf16 v[2:17], v[90:93], v[98:101], v[2:17]
	v_add_u32_e32 v90, 0x1a0a0, v67
	ds_read2_b64 v[90:93], v90 offset1:1
	v_mfma_f32_32x32x16_bf16 v[18:33], v[78:81], v[94:97], v[18:33]
	s_waitcnt lgkmcnt(1)
	v_mfma_f32_32x32x16_bf16 v[50:65], v[86:89], v[94:97], v[50:65]
	ds_read_b128 v[94:97], v69 offset:3904
	v_mfma_f32_32x32x16_bf16 v[34:49], v[74:77], v[98:101], v[34:49]
	v_mfma_f32_32x32x16_bf16 v[18:33], v[82:85], v[98:101], v[18:33]
	s_waitcnt lgkmcnt(1)
	v_mfma_f32_32x32x16_bf16 v[50:65], v[90:93], v[98:101], v[50:65]
	ds_read_b128 v[98:101], v69 offset:3936
	s_waitcnt lgkmcnt(1)
	v_mfma_f32_32x32x16_bf16 v[2:17], v[78:81], v[94:97], v[2:17]
	v_add_u32_e32 v78, 0x1a0c0, v67
	ds_read2_b64 v[78:81], v78 offset1:1
	v_mfma_f32_32x32x16_bf16 v[34:49], v[86:89], v[94:97], v[34:49]
	s_waitcnt lgkmcnt(1)
	v_mfma_f32_32x32x16_bf16 v[2:17], v[82:85], v[98:101], v[2:17]
	v_add_u32_e32 v82, 0x1a0e0, v67
	ds_read2_b64 v[82:85], v82 offset1:1
	v_mfma_f32_32x32x16_bf16 v[34:49], v[90:93], v[98:101], v[34:49]
	v_mfma_f32_32x32x16_bf16 v[18:33], v[70:73], v[94:97], v[18:33]
	s_waitcnt lgkmcnt(1)
	v_mfma_f32_32x32x16_bf16 v[50:65], v[78:81], v[94:97], v[50:65]
	ds_read_b128 v[94:97], v69 offset:3968
	v_mfma_f32_32x32x16_bf16 v[18:33], v[74:77], v[98:101], v[18:33]
	s_waitcnt lgkmcnt(1)
	v_mfma_f32_32x32x16_bf16 v[50:65], v[82:85], v[98:101], v[50:65]
	ds_read_b128 v[98:101], v69 offset:4000
	s_waitcnt lgkmcnt(1)
	v_mfma_f32_32x32x16_bf16 v[34:49], v[78:81], v[94:97], v[34:49]
	v_mfma_f32_32x32x16_bf16 v[2:17], v[70:73], v[94:97], v[2:17]
	v_add_u32_e32 v70, 0x1a100, v67
	ds_read2_b64 v[70:73], v70 offset1:1
	s_waitcnt lgkmcnt(1)
	v_mfma_f32_32x32x16_bf16 v[34:49], v[82:85], v[98:101], v[34:49]
	v_mfma_f32_32x32x16_bf16 v[2:17], v[74:77], v[98:101], v[2:17]
	v_add_u32_e32 v74, 0x1a120, v67
	ds_read2_b64 v[74:77], v74 offset1:1
	v_mfma_f32_32x32x16_bf16 v[18:33], v[86:89], v[94:97], v[18:33]
	s_waitcnt lgkmcnt(1)
	v_mfma_f32_32x32x16_bf16 v[50:65], v[70:73], v[94:97], v[50:65]
	ds_read_b128 v[94:97], v69 offset:4032
	s_waitcnt lgkmcnt(0)
	v_mfma_f32_32x32x16_bf16 v[34:49], v[70:73], v[94:97], v[34:49]
	ds_read_b128 v[70:73], v69 offset:4064
	v_add_u32_e32 v69, 0x1a140, v67
	v_add_u32_e32 v67, 0x1a160, v67
	v_mfma_f32_32x32x16_bf16 v[50:65], v[74:77], v[98:101], v[50:65]
	s_waitcnt lgkmcnt(0)
	v_mfma_f32_32x32x16_bf16 v[34:49], v[74:77], v[70:73], v[34:49]
	ds_read2_b64 v[74:77], v69 offset1:1
	v_mfma_f32_32x32x16_bf16 v[18:33], v[90:93], v[98:101], v[18:33]
	s_waitcnt lgkmcnt(0)
	v_mfma_f32_32x32x16_bf16 v[50:65], v[74:77], v[94:97], v[50:65]
	ds_read2_b64 v[74:77], v67 offset1:1
	v_mfma_f32_32x32x16_bf16 v[18:33], v[78:81], v[94:97], v[18:33]
	v_mfma_f32_32x32x16_bf16 v[2:17], v[86:89], v[94:97], v[2:17]
	v_mfma_f32_32x32x16_bf16 v[18:33], v[82:85], v[70:73], v[18:33]
	v_mfma_f32_32x32x16_bf16 v[2:17], v[90:93], v[70:73], v[2:17]
	s_waitcnt lgkmcnt(0)
	v_mfma_f32_32x32x16_bf16 v[50:65], v[74:77], v[70:73], v[50:65]
	s_and_saveexec_b64 s[6:7], vcc
	s_cbranch_execz .LBB0_704
	v_mad_i64_i32 v[70:71], s[8:9], s18, 24, v[114:115]
	v_lshlrev_b64 v[70:71], 12, v[70:71]
	v_lshl_add_u64 v[70:71], s[0:1], 0, v[70:71]
	v_ashrrev_i32_e32 v67, 31, v66
	v_lshl_add_u64 v[66:67], v[66:67], 1, v[70:71]
	v_lshlrev_b32_e32 v114, 3, v68
	v_lshl_add_u64 v[66:67], v[66:67], 0, v[114:115]
	v_cvt_pk_bf16_f32 v50, v50, v51
	v_cvt_pk_bf16_f32 v51, v52, v53
	s_nop 2
	global_store_dwordx2 v[66:67], v[50:51], off
	v_cvt_pk_bf16_f32 v50, v54, v55
	v_cvt_pk_bf16_f32 v51, v56, v57
	global_store_dwordx2 v[66:67], v[50:51], off offset:16
	v_cvt_pk_bf16_f32 v50, v58, v59
	v_cvt_pk_bf16_f32 v51, v60, v61
	global_store_dwordx2 v[66:67], v[50:51], off offset:32
	v_cvt_pk_bf16_f32 v50, v62, v63
	v_cvt_pk_bf16_f32 v51, v64, v65
	global_store_dwordx2 v[66:67], v[50:51], off offset:48
	v_cvt_pk_bf16_f32 v34, v34, v35
	v_cvt_pk_bf16_f32 v35, v36, v37
	global_store_dwordx2 v[66:67], v[34:35], off offset:64
	v_cvt_pk_bf16_f32 v34, v38, v39
	v_cvt_pk_bf16_f32 v35, v40, v41
	global_store_dwordx2 v[66:67], v[34:35], off offset:80
	v_cvt_pk_bf16_f32 v34, v42, v43
	v_cvt_pk_bf16_f32 v35, v44, v45
	global_store_dwordx2 v[66:67], v[34:35], off offset:96
	v_cvt_pk_bf16_f32 v34, v46, v47
	v_cvt_pk_bf16_f32 v35, v48, v49
	global_store_dwordx2 v[66:67], v[34:35], off offset:112
	v_cvt_pk_bf16_f32 v18, v18, v19
	v_cvt_pk_bf16_f32 v19, v20, v21
	global_store_dwordx2 v[66:67], v[18:19], off offset:128
	v_cvt_pk_bf16_f32 v18, v22, v23
	v_cvt_pk_bf16_f32 v19, v24, v25
	global_store_dwordx2 v[66:67], v[18:19], off offset:144
	v_cvt_pk_bf16_f32 v18, v26, v27
	v_cvt_pk_bf16_f32 v19, v28, v29
	global_store_dwordx2 v[66:67], v[18:19], off offset:160
	v_cvt_pk_bf16_f32 v18, v30, v31
	v_cvt_pk_bf16_f32 v19, v32, v33
	global_store_dwordx2 v[66:67], v[18:19], off offset:176
	v_cvt_pk_bf16_f32 v2, v2, v3
	v_cvt_pk_bf16_f32 v3, v4, v5
	global_store_dwordx2 v[66:67], v[2:3], off offset:192
	v_cvt_pk_bf16_f32 v2, v6, v7
	v_cvt_pk_bf16_f32 v3, v8, v9
	global_store_dwordx2 v[66:67], v[2:3], off offset:208
	v_cvt_pk_bf16_f32 v2, v10, v11
	v_cvt_pk_bf16_f32 v3, v12, v13
	global_store_dwordx2 v[66:67], v[2:3], off offset:224
	v_cvt_pk_bf16_f32 v2, v14, v15
	v_cvt_pk_bf16_f32 v3, v16, v17
	global_store_dwordx2 v[66:67], v[2:3], off offset:240
	s_branch .LBB0_704
